# v46 + attention loops: cross-half max exchange via v_permlane32_swap instead of ds_bpermute, adjacent in-place f32 subtractions packed into v_pk_add_f32 (neg)
# baseline (speedup 1.0000x reference)
.LBB0_567:
	v_max_f32_e32 v0, v51, v51
	s_nop 7
	v_max_f32_e32 v66, v50, v50
	v_max_f32_e32 v0, v66, v0
	v_max3_f32 v0, v0, v52, v53
	v_max3_f32 v0, v0, v54, v55
	v_max3_f32 v0, v0, v56, v57
	v_max3_f32 v0, v0, v58, v59
	v_max3_f32 v0, v0, v60, v61
	v_max3_f32 v0, v0, v62, v63
	v_max3_f32 v0, v0, v64, v65
	v_fmac_f32_e32 v0, 0x40c00000, v99
	v_mov_b32_e32 v66, v0
	s_nop 1
	v_permlane32_swap_b32_e32 v0, v66
	s_waitcnt lgkmcnt(0)
	v_max3_f32 v104, v101, v0, v66
	v_cmp_gt_f32_e32 vcc, v104, v101
	s_cbranch_vccz .LBB0_576
	v_sub_f32_e32 v0, v101, v104
	v_exp_f32_e32 v0, v0
	s_andn2_b64 vcc, exec, s[4:5]
	s_cbranch_vccnz .LBB0_570
	v_pk_mul_f32 v[120:121], v[120:121], v[0:1] op_sel_hi:[1,0]
	v_mul_f32_e32 v112, v112, v0
	v_pk_mul_f32 v[110:111], v[110:111], v[0:1] op_sel_hi:[1,0]
	v_mov_b32_e32 v122, v121
	v_mov_b32_e32 v123, v121

.LBB0_587:
	v_max_f32_e32 v0, v51, v51
	s_nop 7
	v_max_f32_e32 v66, v50, v50
	v_max_f32_e32 v0, v66, v0
	v_max3_f32 v0, v0, v52, v53
	v_max3_f32 v0, v0, v54, v55
	v_max3_f32 v0, v0, v56, v57
	v_max3_f32 v0, v0, v58, v59
	v_max3_f32 v0, v0, v60, v61
	v_max3_f32 v0, v0, v62, v63
	v_max3_f32 v0, v0, v64, v65
	v_fmac_f32_e32 v0, 0x40a00000, v99
	v_mov_b32_e32 v66, v0
	s_nop 1
	v_permlane32_swap_b32_e32 v0, v66
	s_waitcnt lgkmcnt(0)
	v_max3_f32 v101, v104, v0, v66
	v_cmp_gt_f32_e32 vcc, v101, v104
	s_cbranch_vccz .LBB0_591
	v_sub_f32_e32 v0, v104, v101
	v_exp_f32_e32 v0, v0
	s_andn2_b64 vcc, exec, s[4:5]
	s_cbranch_vccnz .LBB0_590
	v_pk_mul_f32 v[112:113], v[112:113], v[0:1] op_sel_hi:[1,0]
	v_pk_mul_f32 v[122:123], v[122:123], v[0:1] op_sel_hi:[1,0]
	v_mul_f32_e32 v124, v124, v0
	v_pk_mul_f32 v[120:121], v[120:121], v[0:1] op_sel_hi:[1,0]
	v_pk_mul_f32 v[110:111], v[110:111], v[0:1] op_sel_hi:[1,0]
	v_mov_b32_e32 v126, v113
	v_mov_b32_e32 v127, v113

.LBB0_600:
	v_max_f32_e32 v0, v51, v51
	s_nop 7
	v_max_f32_e32 v66, v50, v50
	v_max_f32_e32 v0, v66, v0
	v_max3_f32 v0, v0, v52, v53
	v_max3_f32 v0, v0, v54, v55
	v_max3_f32 v0, v0, v56, v57
	v_max3_f32 v0, v0, v58, v59
	v_max3_f32 v0, v0, v60, v61
	v_max3_f32 v0, v0, v62, v63
	v_max3_f32 v0, v0, v64, v65
	v_fmac_f32_e32 v0, 4.0, v99
	v_mov_b32_e32 v66, v0
	s_nop 1
	v_permlane32_swap_b32_e32 v0, v66
	s_waitcnt lgkmcnt(0)
	v_max3_f32 v104, v101, v0, v66
	v_cmp_gt_f32_e32 vcc, v104, v101
	s_cbranch_vccz .LBB0_604
	v_sub_f32_e32 v0, v101, v104
	v_exp_f32_e32 v0, v0
	s_andn2_b64 vcc, exec, s[4:5]
	s_cbranch_vccnz .LBB0_603
	v_pk_mul_f32 v[112:113], v[112:113], v[0:1] op_sel_hi:[1,0]
	v_mul_f32_e32 v129, v129, v0
	v_pk_mul_f32 v[126:127], v[126:127], v[0:1] op_sel_hi:[1,0]
	v_pk_mul_f32 v[122:123], v[122:123], v[0:1] op_sel_hi:[1,0]
	v_pk_mul_f32 v[124:125], v[124:125], v[0:1] op_sel_hi:[1,0]
	v_pk_mul_f32 v[120:121], v[120:121], v[0:1] op_sel_hi:[1,0]
	v_pk_mul_f32 v[110:111], v[110:111], v[0:1] op_sel_hi:[1,0]
	v_mov_b32_e32 v130, v113
	v_mov_b32_e32 v131, v113

.LBB0_614:
	v_max_f32_e32 v0, v51, v51
	s_nop 7
	v_max_f32_e32 v66, v50, v50
	v_max_f32_e32 v0, v66, v0
	v_max3_f32 v0, v0, v52, v53
	v_max3_f32 v0, v0, v54, v55
	v_max3_f32 v0, v0, v56, v57
	v_max3_f32 v0, v0, v58, v59
	v_max3_f32 v0, v0, v60, v61
	v_max3_f32 v0, v0, v62, v63
	v_max3_f32 v0, v0, v64, v65
	v_fmac_f32_e32 v0, 0x40400000, v99
	v_mov_b32_e32 v66, v0
	s_nop 1
	v_permlane32_swap_b32_e32 v0, v66
	s_waitcnt lgkmcnt(0)
	v_max3_f32 v101, v104, v0, v66
	v_cmp_gt_f32_e32 vcc, v101, v104
	s_cbranch_vccz .LBB0_618
	v_sub_f32_e32 v0, v104, v101
	v_exp_f32_e32 v0, v0
	s_andn2_b64 vcc, exec, s[4:5]
	s_cbranch_vccnz .LBB0_617
	v_pk_mul_f32 v[130:131], v[130:131], v[0:1] op_sel_hi:[1,0]
	v_pk_mul_f32 v[132:133], v[132:133], v[0:1] op_sel_hi:[1,0]
	v_pk_mul_f32 v[126:127], v[126:127], v[0:1] op_sel_hi:[1,0]
	v_pk_mul_f32 v[128:129], v[128:129], v[0:1] op_sel_hi:[1,0]
	v_pk_mul_f32 v[122:123], v[122:123], v[0:1] op_sel_hi:[1,0]
	v_pk_mul_f32 v[124:125], v[124:125], v[0:1] op_sel_hi:[1,0]
	v_mul_f32_e32 v120, v120, v0
	v_pk_mul_f32 v[110:111], v[110:111], v[0:1] op_sel_hi:[1,0]
	v_pk_mul_f32 v[112:113], v[112:113], v[0:1] op_sel_hi:[1,0]
	v_mov_b32_e32 v134, v131
	v_mov_b32_e32 v135, v131

.LBB0_628:
	v_max_f32_e32 v0, v51, v51
	s_nop 7
	v_max_f32_e32 v66, v50, v50
	v_max_f32_e32 v0, v66, v0
	v_max3_f32 v0, v0, v52, v53
	v_max3_f32 v0, v0, v54, v55
	v_max3_f32 v0, v0, v56, v57
	v_max3_f32 v0, v0, v58, v59
	v_max3_f32 v0, v0, v60, v61
	v_max3_f32 v0, v0, v62, v63
	v_max3_f32 v0, v0, v64, v65
	v_fmac_f32_e32 v0, 2.0, v99
	v_mov_b32_e32 v66, v0
	s_nop 1
	v_permlane32_swap_b32_e32 v0, v66
	s_waitcnt lgkmcnt(0)
	v_max3_f32 v105, v101, v0, v66
	v_cmp_gt_f32_e32 vcc, v105, v101
	s_cbranch_vccz .LBB0_632
	v_sub_f32_e32 v0, v101, v105
	v_exp_f32_e32 v0, v0
	s_andn2_b64 vcc, exec, s[4:5]
	s_cbranch_vccnz .LBB0_631
	v_pk_mul_f32 v[134:135], v[134:135], v[0:1] op_sel_hi:[1,0]
	v_pk_mul_f32 v[138:139], v[138:139], v[0:1] op_sel_hi:[1,0]
	v_pk_mul_f32 v[130:131], v[130:131], v[0:1] op_sel_hi:[1,0]
	v_pk_mul_f32 v[132:133], v[132:133], v[0:1] op_sel_hi:[1,0]
	v_pk_mul_f32 v[126:127], v[126:127], v[0:1] op_sel_hi:[1,0]
	v_pk_mul_f32 v[128:129], v[128:129], v[0:1] op_sel_hi:[1,0]
	v_pk_mul_f32 v[122:123], v[122:123], v[0:1] op_sel_hi:[1,0]
	v_pk_mul_f32 v[124:125], v[124:125], v[0:1] op_sel_hi:[1,0]
	v_mul_f32_e32 v120, v120, v0
	v_pk_mul_f32 v[110:111], v[110:111], v[0:1] op_sel_hi:[1,0]
	v_pk_mul_f32 v[112:113], v[112:113], v[0:1] op_sel_hi:[1,0]
	v_mov_b32_e32 v142, v135
	v_mov_b32_e32 v143, v135

.LBB0_644:
	v_max_f32_e32 v0, v51, v51
	s_nop 7
	v_max_f32_e32 v66, v50, v50
	v_max_f32_e32 v0, v66, v0
	v_max3_f32 v0, v0, v52, v53
	v_max3_f32 v0, v0, v54, v55
	v_max3_f32 v0, v0, v56, v57
	v_max3_f32 v0, v0, v58, v59
	v_max3_f32 v0, v0, v60, v61
	v_max3_f32 v0, v0, v62, v63
	v_max3_f32 v0, v0, v64, v65
	v_add_f32_e32 v0, v99, v0
	v_mov_b32_e32 v66, v0
	s_nop 1
	v_permlane32_swap_b32_e32 v0, v66
	s_waitcnt lgkmcnt(0)
	v_max3_f32 v104, v105, v0, v66
	v_cmp_gt_f32_e32 vcc, v104, v105
	s_cbranch_vccz .LBB0_648
	v_sub_f32_e32 v0, v105, v104
	v_exp_f32_e32 v0, v0
	s_andn2_b64 vcc, exec, s[4:5]
	s_cbranch_vccnz .LBB0_647
	v_pk_mul_f32 v[142:143], v[142:143], v[0:1] op_sel_hi:[1,0]
	v_pk_mul_f32 v[144:145], v[144:145], v[0:1] op_sel_hi:[1,0]
	v_pk_mul_f32 v[134:135], v[134:135], v[0:1] op_sel_hi:[1,0]
	v_pk_mul_f32 v[138:139], v[138:139], v[0:1] op_sel_hi:[1,0]
	v_pk_mul_f32 v[130:131], v[130:131], v[0:1] op_sel_hi:[1,0]
	v_pk_mul_f32 v[132:133], v[132:133], v[0:1] op_sel_hi:[1,0]
	v_pk_mul_f32 v[126:127], v[126:127], v[0:1] op_sel_hi:[1,0]
	v_pk_mul_f32 v[128:129], v[128:129], v[0:1] op_sel_hi:[1,0]
	v_pk_mul_f32 v[122:123], v[122:123], v[0:1] op_sel_hi:[1,0]
	v_pk_mul_f32 v[124:125], v[124:125], v[0:1] op_sel_hi:[1,0]
	v_mul_f32_e32 v120, v120, v0
	v_pk_mul_f32 v[110:111], v[110:111], v[0:1] op_sel_hi:[1,0]
	v_pk_mul_f32 v[112:113], v[112:113], v[0:1] op_sel_hi:[1,0]

.LBB0_690:
	v_lshrrev_b64 v[142:143], s73, v[148:149]
	v_and_b32_e32 v139, 1, v142
	v_cmp_eq_u32_e64 s[0:1], 1, v139
	s_nop 5
	v_max_f32_e32 v139, v67, v67
	v_max_f32_e32 v144, v66, v66
	v_max_f32_e32 v139, v144, v139
	v_max_f32_e32 v144, v51, v51
	v_max_f32_e32 v145, v50, v50
	v_max_f32_e32 v144, v145, v144
	v_max3_f32 v139, v139, v68, v69
	v_max3_f32 v144, v144, v52, v53
	s_lshl_b32 s73, s73, 6
	v_max3_f32 v139, v139, v70, v71
	v_max3_f32 v144, v144, v54, v55
	v_cvt_f32_i32_e32 v143, s73
	v_max3_f32 v139, v139, v72, v73
	v_max3_f32 v144, v144, v56, v57
	v_max3_f32 v139, v139, v74, v75
	v_max3_f32 v144, v144, v58, v59
	v_max3_f32 v139, v139, v76, v77
	v_max3_f32 v144, v144, v60, v61
	v_max3_f32 v139, v139, v78, v79
	v_max3_f32 v144, v144, v62, v63
	v_fma_f32 v142, v118, v143, v128
	v_max3_f32 v139, v139, v80, v81
	v_max3_f32 v144, v144, v64, v65
	v_fmac_f32_e32 v139, v118, v143
	v_add_f32_e32 v144, v142, v144
	v_max_f32_e32 v139, v139, v144
	v_cndmask_b32_e64 v139, v158, v139, s[0:1]
	v_mov_b32_e32 v144, v139
	s_nop 1
	v_permlane32_swap_b32_e32 v139, v144
	s_waitcnt lgkmcnt(0)
	v_max_f32_e32 v144, v144, v144
	v_max_f32_e32 v139, v139, v144
	v_add_f32_e32 v144, 0xc1c00000, v138
	v_cmp_gt_f32_e32 vcc, v139, v144
	s_cbranch_vccz .LBB0_694
	v_max_f32_e32 v139, v139, v139
	v_max_f32_e32 v144, v138, v138
	v_max_f32_e32 v139, v144, v139
	v_cmp_gt_f32_e32 vcc, v139, v138
	s_cbranch_vccz .LBB0_693
	v_sub_f32_e32 v138, v138, v139
	v_exp_f32_e32 v138, v138
	s_nop 0
	v_mul_f32_e32 v134, v134, v138
	v_pk_mul_f32 v[32:33], v[32:33], v[138:139] op_sel_hi:[1,0]
	v_pk_mul_f32 v[30:31], v[30:31], v[138:139] op_sel_hi:[1,0]
	v_pk_mul_f32 v[28:29], v[28:29], v[138:139] op_sel_hi:[1,0]
	v_pk_mul_f32 v[26:27], v[26:27], v[138:139] op_sel_hi:[1,0]
	v_pk_mul_f32 v[24:25], v[24:25], v[138:139] op_sel_hi:[1,0]
	v_pk_mul_f32 v[22:23], v[22:23], v[138:139] op_sel_hi:[1,0]
	v_pk_mul_f32 v[20:21], v[20:21], v[138:139] op_sel_hi:[1,0]
	v_pk_mul_f32 v[18:19], v[18:19], v[138:139] op_sel_hi:[1,0]
	v_pk_mul_f32 v[16:17], v[16:17], v[138:139] op_sel_hi:[1,0]
	v_pk_mul_f32 v[14:15], v[14:15], v[138:139] op_sel_hi:[1,0]
	v_pk_mul_f32 v[12:13], v[12:13], v[138:139] op_sel_hi:[1,0]
	v_pk_mul_f32 v[10:11], v[10:11], v[138:139] op_sel_hi:[1,0]
	v_pk_mul_f32 v[8:9], v[8:9], v[138:139] op_sel_hi:[1,0]
	v_pk_mul_f32 v[6:7], v[6:7], v[138:139] op_sel_hi:[1,0]
	v_pk_mul_f32 v[4:5], v[4:5], v[138:139] op_sel_hi:[1,0]
	v_pk_mul_f32 v[2:3], v[2:3], v[138:139] op_sel_hi:[1,0]
.LBB0_693:
	v_mul_f32_e32 v138, v118, v143
	v_cmp_lt_f32_e32 vcc, s33, v139
	v_sub_f32_e32 v138, v139, v138
	s_and_b64 vcc, s[0:1], vcc
	v_sub_f32_e32 v142, v139, v142
	v_cndmask_b32_e32 v138, v159, v138, vcc
	v_cndmask_b32_e32 v142, v159, v142, vcc
	v_pk_add_f32 v[68:69], v[68:69], v[138:139] op_sel_hi:[1,0] neg_lo:[0,1] neg_hi:[0,1]
	v_pk_add_f32 v[66:67], v[66:67], v[138:139] op_sel_hi:[1,0] neg_lo:[0,1] neg_hi:[0,1]
	v_pk_add_f32 v[52:53], v[52:53], v[142:143] op_sel_hi:[1,0] neg_lo:[0,1] neg_hi:[0,1]
	v_pk_add_f32 v[50:51], v[50:51], v[142:143] op_sel_hi:[1,0] neg_lo:[0,1] neg_hi:[0,1]
	v_add_u32_e32 v175, s86, v130
	v_sub_f32_e32 v143, v81, v138
	v_sub_f32_e32 v145, v80, v138
	v_sub_f32_e32 v147, v79, v138
	v_sub_f32_e32 v146, v78, v138
	v_sub_f32_e32 v169, v77, v138
	v_sub_f32_e32 v144, v76, v138
	v_sub_f32_e32 v79, v75, v138
	v_sub_f32_e32 v78, v74, v138
	v_sub_f32_e32 v75, v73, v138
	v_sub_f32_e32 v74, v72, v138
	v_pk_add_f32 v[70:71], v[70:71], v[138:139] op_sel_hi:[1,0] neg_lo:[0,1] neg_hi:[0,1]
	v_sub_f32_e32 v138, v65, v142
	v_sub_f32_e32 v151, v64, v142
	v_sub_f32_e32 v172, v63, v142
	v_sub_f32_e32 v150, v62, v142
	v_exp_f32_e32 v62, v66
	v_exp_f32_e32 v64, v50
	v_exp_f32_e32 v63, v67
	v_exp_f32_e32 v65, v51
	v_exp_f32_e32 v66, v68
	v_exp_f32_e32 v68, v52
	v_exp_f32_e32 v67, v69
	v_exp_f32_e32 v69, v53
	ds_read2_b64 v[50:53], v175 offset1:2
	v_sub_f32_e32 v60, v60, v142
	v_pk_add_f32 v[58:59], v[58:59], v[142:143] op_sel_hi:[1,0] neg_lo:[0,1] neg_hi:[0,1]
	v_add_u32_e32 v182, 0x1000, v175
	v_sub_f32_e32 v173, v61, v142
	v_pk_add_f32 v[56:57], v[56:57], v[142:143] op_sel_hi:[1,0] neg_lo:[0,1] neg_hi:[0,1]
	v_pk_add_f32 v[54:55], v[54:55], v[142:143] op_sel_hi:[1,0] neg_lo:[0,1] neg_hi:[0,1]
	v_exp_f32_e32 v80, v58
	v_exp_f32_e32 v81, v59
	v_exp_f32_e32 v142, v144
	v_exp_f32_e32 v144, v60
	ds_read2_b64 v[58:61], v182 offset0:32 offset1:34
	v_exp_f32_e32 v70, v70
	v_exp_f32_e32 v71, v71
	v_exp_f32_e32 v74, v74
	v_exp_f32_e32 v75, v75
	v_exp_f32_e32 v72, v54
	v_exp_f32_e32 v73, v55
	v_exp_f32_e32 v76, v56
	v_exp_f32_e32 v77, v57
	v_cvt_pk_bf16_f32 v54, v62, v63
	v_cvt_pk_bf16_f32 v55, v66, v67
	v_cvt_pk_bf16_f32 v56, v70, v71
	v_cvt_pk_bf16_f32 v57, v74, v75
	v_exp_f32_e32 v78, v78
	v_exp_f32_e32 v79, v79
	s_waitcnt lgkmcnt(1)
	v_mfma_f32_32x32x16_bf16 v[18:33], v[50:53], v[54:57], v[18:33]
	ds_read2_b64 v[50:53], v175 offset0:4 offset1:6
	v_exp_f32_e32 v146, v146
	v_exp_f32_e32 v147, v147
	v_exp_f32_e32 v152, v145
	v_exp_f32_e32 v153, v143
	v_exp_f32_e32 v143, v169
	v_pk_add_f32 v[62:63], v[62:63], v[64:65]
	s_waitcnt lgkmcnt(1)
	v_mfma_f32_32x32x16_bf16 v[2:17], v[58:61], v[54:57], v[2:17]
	ds_read2_b64 v[58:61], v182 offset0:36 offset1:38
	v_cvt_pk_bf16_f32 v54, v78, v79
	v_cvt_pk_bf16_f32 v55, v142, v143
	v_cvt_pk_bf16_f32 v56, v146, v147
	v_cvt_pk_bf16_f32 v57, v152, v153
	v_pk_add_f32 v[74:75], v[74:75], v[76:77]
	v_pk_add_f32 v[70:71], v[70:71], v[72:73]
	s_waitcnt lgkmcnt(1)
	v_mfma_f32_32x32x16_bf16 v[18:33], v[50:53], v[54:57], v[18:33]
	v_add_f32_e64 v50, v66, v68
	v_add_f32_e64 v51, v67, v69
	v_exp_f32_e32 v150, v150
	v_pk_mov_b32 v[66:67], v[62:63], v[50:51] op_sel:[1,0]
	v_mov_b32_e32 v63, v51
	ds_read2_b64 v[50:53], v175 offset0:8 offset1:10
	v_exp_f32_e32 v170, v151
	v_exp_f32_e32 v171, v138
	s_waitcnt lgkmcnt(1)
	v_mfma_f32_32x32x16_bf16 v[2:17], v[58:61], v[54:57], v[2:17]
	ds_read2_b64 v[58:61], v182 offset0:40 offset1:42
	v_add_f32_e64 v54, v66, v62
	v_add_f32_e64 v55, v67, v63
	v_cvt_pk_bf16_f32 v56, v72, v73
	v_add_f32_e64 v62, v54, v54
	v_add_f32_e64 v63, v54, v55
	v_cvt_pk_bf16_f32 v54, v64, v65
	v_cvt_pk_bf16_f32 v55, v68, v69
	v_cvt_pk_bf16_f32 v57, v76, v77
	v_exp_f32_e32 v151, v172
	v_exp_f32_e32 v145, v173
	s_waitcnt lgkmcnt(1)
	v_mfma_f32_32x32x16_bf16 v[18:33], v[50:53], v[54:57], v[18:33]
	v_pk_mov_b32 v[50:51], v[70:71], v[74:75] op_sel:[1,0]
	v_mov_b32_e32 v71, v75
	v_pk_add_f32 v[50:51], v[50:51], v[70:71]
	v_pk_add_f32 v[172:173], v[152:153], v[170:171]
	v_pk_add_f32 v[64:65], v[50:51], v[50:51] op_sel_hi:[0,1]
	ds_read2_b64 v[50:53], v175 offset0:12 offset1:14
	v_pk_add_f32 v[176:177], v[146:147], v[150:151]
	s_waitcnt lgkmcnt(1)
	v_mfma_f32_32x32x16_bf16 v[2:17], v[58:61], v[54:57], v[2:17]
	ds_read2_b64 v[58:61], v182 offset0:44 offset1:46
	v_cvt_pk_bf16_f32 v54, v80, v81
	v_cvt_pk_bf16_f32 v55, v144, v145
	v_cvt_pk_bf16_f32 v56, v150, v151
	v_cvt_pk_bf16_f32 v57, v170, v171
	v_pk_add_f32 v[178:179], v[142:143], v[144:145]
	v_pk_add_f32 v[180:181], v[78:79], v[80:81]
	s_waitcnt lgkmcnt(1)
	v_mfma_f32_32x32x16_bf16 v[18:33], v[50:53], v[54:57], v[18:33]
	v_add_f32_e32 v67, v180, v181
	v_add_f32_e32 v69, v178, v179
	v_mov_b32_e32 v66, v176
	v_mov_b32_e32 v68, v177
	v_mov_b32_e32 v62, v172
	v_mov_b32_e32 v64, v173
	v_pk_add_f32 v[50:51], v[66:67], v[68:69]
	s_waitcnt lgkmcnt(0)
	v_mfma_f32_32x32x16_bf16 v[2:17], v[58:61], v[54:57], v[2:17]
	v_add_f32_e64 v52, v62, v64
	v_add_f32_e64 v53, v63, v65
	v_add_f32_e64 v50, v50, v52
	v_add_f32_e64 v51, v51, v53
	v_add_f32_e32 v50, v50, v51
	v_add_f32_e32 v134, v50, v134
	s_branch .LBB0_695

.LBB0_702:
	v_lshrrev_b64 v[142:143], s77, v[148:149]
	v_and_b32_e32 v138, 1, v142
	v_cmp_eq_u32_e64 s[0:1], 1, v138
	s_nop 5
	v_max_f32_e32 v138, v67, v67
	v_max_f32_e32 v144, v66, v66
	v_max_f32_e32 v138, v144, v138
	v_max_f32_e32 v144, v51, v51
	v_max_f32_e32 v145, v50, v50
	v_max_f32_e32 v144, v145, v144
	v_max3_f32 v138, v138, v68, v69
	v_max3_f32 v144, v144, v52, v53
	s_lshl_b32 s77, s77, 6
	v_max3_f32 v138, v138, v70, v71
	v_max3_f32 v144, v144, v54, v55
	v_cvt_f32_u32_e32 v143, s77
	v_max3_f32 v138, v138, v72, v73
	v_max3_f32 v144, v144, v56, v57
	v_max3_f32 v138, v138, v74, v75
	v_max3_f32 v144, v144, v58, v59
	v_max3_f32 v138, v138, v76, v77
	v_max3_f32 v144, v144, v60, v61
	v_max3_f32 v138, v138, v78, v79
	v_max3_f32 v144, v144, v62, v63
	v_fma_f32 v142, v118, v143, v128
	v_max3_f32 v138, v138, v80, v81
	v_max3_f32 v144, v144, v64, v65
	v_fmac_f32_e32 v138, v118, v143
	v_add_f32_e32 v144, v142, v144
	v_max_f32_e32 v138, v138, v144
	v_cndmask_b32_e64 v138, v158, v138, s[0:1]
	v_mov_b32_e32 v144, v138
	s_nop 1
	v_permlane32_swap_b32_e32 v138, v144
	s_waitcnt lgkmcnt(0)
	v_max_f32_e32 v144, v144, v144
	v_max_f32_e32 v138, v138, v144
	v_add_f32_e32 v144, 0xc1c00000, v139
	v_cmp_gt_f32_e32 vcc, v138, v144
	s_cbranch_vccz .LBB0_706
	v_max_f32_e32 v138, v138, v138
	v_max_f32_e32 v144, v139, v139
	v_max_f32_e32 v138, v144, v138
	v_cmp_gt_f32_e32 vcc, v138, v139
	s_cbranch_vccz .LBB0_705
	v_sub_f32_e32 v139, v139, v138
	v_exp_f32_e32 v144, v139
	s_nop 0
	v_mul_f32_e32 v134, v134, v144
	v_pk_mul_f32 v[32:33], v[32:33], v[144:145] op_sel_hi:[1,0]
	v_pk_mul_f32 v[30:31], v[30:31], v[144:145] op_sel_hi:[1,0]
	v_pk_mul_f32 v[28:29], v[28:29], v[144:145] op_sel_hi:[1,0]
	v_pk_mul_f32 v[26:27], v[26:27], v[144:145] op_sel_hi:[1,0]
	v_pk_mul_f32 v[24:25], v[24:25], v[144:145] op_sel_hi:[1,0]
	v_pk_mul_f32 v[22:23], v[22:23], v[144:145] op_sel_hi:[1,0]
	v_pk_mul_f32 v[20:21], v[20:21], v[144:145] op_sel_hi:[1,0]
	v_pk_mul_f32 v[18:19], v[18:19], v[144:145] op_sel_hi:[1,0]
	v_pk_mul_f32 v[16:17], v[16:17], v[144:145] op_sel_hi:[1,0]
	v_pk_mul_f32 v[14:15], v[14:15], v[144:145] op_sel_hi:[1,0]
	v_pk_mul_f32 v[12:13], v[12:13], v[144:145] op_sel_hi:[1,0]
	v_pk_mul_f32 v[10:11], v[10:11], v[144:145] op_sel_hi:[1,0]
	v_pk_mul_f32 v[8:9], v[8:9], v[144:145] op_sel_hi:[1,0]
	v_pk_mul_f32 v[6:7], v[6:7], v[144:145] op_sel_hi:[1,0]
	v_pk_mul_f32 v[4:5], v[4:5], v[144:145] op_sel_hi:[1,0]
	v_pk_mul_f32 v[2:3], v[2:3], v[144:145] op_sel_hi:[1,0]
.LBB0_705:
	v_mul_f32_e32 v139, v118, v143
	v_cmp_lt_f32_e32 vcc, s33, v138
	v_sub_f32_e32 v139, v138, v139
	s_and_b64 vcc, s[0:1], vcc
	v_sub_f32_e32 v142, v138, v142
	v_cndmask_b32_e32 v139, v159, v139, vcc
	v_cndmask_b32_e32 v142, v159, v142, vcc
	v_sub_f32_e32 v69, v69, v139
	v_sub_f32_e32 v68, v68, v139
	v_sub_f32_e32 v67, v67, v139
	v_sub_f32_e32 v66, v66, v139
	v_pk_add_f32 v[52:53], v[52:53], v[142:143] op_sel_hi:[1,0] neg_lo:[0,1] neg_hi:[0,1]
	v_pk_add_f32 v[50:51], v[50:51], v[142:143] op_sel_hi:[1,0] neg_lo:[0,1] neg_hi:[0,1]
	v_add_u32_e32 v175, s87, v130
	v_sub_f32_e32 v143, v81, v139
	v_sub_f32_e32 v145, v80, v139
	v_sub_f32_e32 v147, v79, v139
	v_sub_f32_e32 v146, v78, v139
	v_sub_f32_e32 v169, v77, v139
	v_sub_f32_e32 v144, v76, v139
	v_sub_f32_e32 v79, v75, v139
	v_sub_f32_e32 v78, v74, v139
	v_sub_f32_e32 v75, v73, v139
	v_sub_f32_e32 v74, v72, v139
	v_sub_f32_e32 v71, v71, v139
	v_sub_f32_e32 v70, v70, v139
	v_sub_f32_e32 v139, v65, v142
	v_sub_f32_e32 v151, v64, v142
	v_sub_f32_e32 v172, v63, v142
	v_sub_f32_e32 v150, v62, v142
	v_exp_f32_e32 v62, v66
	v_exp_f32_e32 v64, v50
	v_exp_f32_e32 v63, v67
	v_exp_f32_e32 v65, v51
	v_exp_f32_e32 v66, v68
	v_exp_f32_e32 v68, v52
	v_exp_f32_e32 v67, v69
	v_exp_f32_e32 v69, v53
	ds_read2_b64 v[50:53], v175 offset1:2
	v_sub_f32_e32 v60, v60, v142
	v_pk_add_f32 v[58:59], v[58:59], v[142:143] op_sel_hi:[1,0] neg_lo:[0,1] neg_hi:[0,1]
	v_add_u32_e32 v182, 0x1000, v175
	v_sub_f32_e32 v173, v61, v142
	v_pk_add_f32 v[56:57], v[56:57], v[142:143] op_sel_hi:[1,0] neg_lo:[0,1] neg_hi:[0,1]
	v_pk_add_f32 v[54:55], v[54:55], v[142:143] op_sel_hi:[1,0] neg_lo:[0,1] neg_hi:[0,1]
	v_exp_f32_e32 v80, v58
	v_exp_f32_e32 v81, v59
	v_exp_f32_e32 v142, v144
	v_exp_f32_e32 v144, v60
	ds_read2_b64 v[58:61], v182 offset0:32 offset1:34
	v_exp_f32_e32 v70, v70
	v_exp_f32_e32 v71, v71
	v_exp_f32_e32 v74, v74
	v_exp_f32_e32 v75, v75
	v_exp_f32_e32 v72, v54
	v_exp_f32_e32 v73, v55
	v_exp_f32_e32 v76, v56
	v_exp_f32_e32 v77, v57
	v_cvt_pk_bf16_f32 v54, v62, v63
	v_cvt_pk_bf16_f32 v55, v66, v67
	v_cvt_pk_bf16_f32 v56, v70, v71
	v_cvt_pk_bf16_f32 v57, v74, v75
	v_exp_f32_e32 v78, v78
	v_exp_f32_e32 v79, v79
	s_waitcnt lgkmcnt(1)
	v_mfma_f32_32x32x16_bf16 v[18:33], v[50:53], v[54:57], v[18:33]
	ds_read2_b64 v[50:53], v175 offset0:4 offset1:6
	v_exp_f32_e32 v146, v146
	v_exp_f32_e32 v147, v147
	v_exp_f32_e32 v152, v145
	v_exp_f32_e32 v153, v143
	v_exp_f32_e32 v143, v169
	v_pk_add_f32 v[62:63], v[62:63], v[64:65]
	s_waitcnt lgkmcnt(1)
	v_mfma_f32_32x32x16_bf16 v[2:17], v[58:61], v[54:57], v[2:17]
	ds_read2_b64 v[58:61], v182 offset0:36 offset1:38
	v_cvt_pk_bf16_f32 v54, v78, v79
	v_cvt_pk_bf16_f32 v55, v142, v143
	v_cvt_pk_bf16_f32 v56, v146, v147
	v_cvt_pk_bf16_f32 v57, v152, v153
	v_pk_add_f32 v[74:75], v[74:75], v[76:77]
	v_pk_add_f32 v[70:71], v[70:71], v[72:73]
	s_waitcnt lgkmcnt(1)
	v_mfma_f32_32x32x16_bf16 v[18:33], v[50:53], v[54:57], v[18:33]
	v_add_f32_e64 v50, v66, v68
	v_add_f32_e64 v51, v67, v69
	v_exp_f32_e32 v150, v150
	v_pk_mov_b32 v[66:67], v[62:63], v[50:51] op_sel:[1,0]
	v_mov_b32_e32 v63, v51
	ds_read2_b64 v[50:53], v175 offset0:8 offset1:10
	v_exp_f32_e32 v170, v151
	v_exp_f32_e32 v171, v139
	s_waitcnt lgkmcnt(1)
	v_mfma_f32_32x32x16_bf16 v[2:17], v[58:61], v[54:57], v[2:17]
	ds_read2_b64 v[58:61], v182 offset0:40 offset1:42
	v_add_f32_e64 v54, v66, v62
	v_add_f32_e64 v55, v67, v63
	v_cvt_pk_bf16_f32 v56, v72, v73
	v_add_f32_e64 v62, v54, v54
	v_add_f32_e64 v63, v54, v55
	v_cvt_pk_bf16_f32 v54, v64, v65
	v_cvt_pk_bf16_f32 v55, v68, v69
	v_cvt_pk_bf16_f32 v57, v76, v77
	v_exp_f32_e32 v151, v172
	v_exp_f32_e32 v145, v173
	s_waitcnt lgkmcnt(1)
	v_mfma_f32_32x32x16_bf16 v[18:33], v[50:53], v[54:57], v[18:33]
	v_pk_mov_b32 v[50:51], v[70:71], v[74:75] op_sel:[1,0]
	v_mov_b32_e32 v71, v75
	v_pk_add_f32 v[50:51], v[50:51], v[70:71]
	v_pk_add_f32 v[172:173], v[152:153], v[170:171]
	v_pk_add_f32 v[64:65], v[50:51], v[50:51] op_sel_hi:[0,1]
	ds_read2_b64 v[50:53], v175 offset0:12 offset1:14
	v_pk_add_f32 v[176:177], v[146:147], v[150:151]
	s_waitcnt lgkmcnt(1)
	v_mfma_f32_32x32x16_bf16 v[2:17], v[58:61], v[54:57], v[2:17]
	ds_read2_b64 v[58:61], v182 offset0:44 offset1:46
	v_cvt_pk_bf16_f32 v54, v80, v81
	v_cvt_pk_bf16_f32 v55, v144, v145
	v_cvt_pk_bf16_f32 v56, v150, v151
	v_cvt_pk_bf16_f32 v57, v170, v171
	v_pk_add_f32 v[178:179], v[142:143], v[144:145]
	v_pk_add_f32 v[180:181], v[78:79], v[80:81]
	s_waitcnt lgkmcnt(1)
	v_mfma_f32_32x32x16_bf16 v[18:33], v[50:53], v[54:57], v[18:33]
	v_add_f32_e32 v67, v180, v181
	v_add_f32_e32 v69, v178, v179
	v_mov_b32_e32 v66, v176
	v_mov_b32_e32 v68, v177
	v_mov_b32_e32 v62, v172
	v_mov_b32_e32 v64, v173
	v_pk_add_f32 v[50:51], v[66:67], v[68:69]
	s_waitcnt lgkmcnt(0)
	v_mfma_f32_32x32x16_bf16 v[2:17], v[58:61], v[54:57], v[2:17]
	v_add_f32_e64 v52, v62, v64
	v_add_f32_e64 v53, v63, v65
	v_add_f32_e64 v50, v50, v52
	v_add_f32_e64 v51, v51, v53
	v_add_f32_e32 v50, v50, v51
	v_add_f32_e32 v134, v50, v134
	s_branch .LBB0_707

.LBB0_725:
	s_nop 8
	v_max_f32_e32 v0, v67, v67
	v_max_f32_e32 v133, v66, v66
	v_max_f32_e32 v134, v51, v51
	v_max_f32_e32 v136, v50, v50
	v_max_f32_e32 v0, v133, v0
	v_max_f32_e32 v134, v136, v134
	v_max3_f32 v0, v0, v68, v69
	v_max3_f32 v134, v134, v52, v53
	s_lshl_b32 s0, s5, 6
	v_max3_f32 v0, v0, v70, v71
	v_max3_f32 v134, v134, v54, v55
	v_cvt_f32_i32_e32 v125, s0
	v_max3_f32 v0, v0, v72, v73
	v_max3_f32 v134, v134, v56, v57
	v_max3_f32 v0, v0, v74, v75
	v_max3_f32 v134, v134, v58, v59
	v_max3_f32 v0, v0, v76, v77
	v_max3_f32 v134, v134, v60, v61
	v_max3_f32 v0, v0, v78, v79
	v_max3_f32 v134, v134, v62, v63
	v_fma_f32 v133, v118, v125, v128
	v_max3_f32 v0, v0, v80, v81
	v_max3_f32 v134, v134, v64, v65
	v_fmac_f32_e32 v0, v118, v125
	v_add_f32_e32 v134, v133, v134
	v_max_f32_e32 v0, v0, v134
	v_mov_b32_e32 v134, v0
	s_nop 1
	v_permlane32_swap_b32_e32 v0, v134
	s_waitcnt lgkmcnt(0)
	v_max_f32_e32 v134, v134, v134
	v_max_f32_e32 v0, v0, v134
	v_add_f32_e32 v134, 0xc1c00000, v124
	v_cmp_gt_f32_e32 vcc, v0, v134
	s_cbranch_vccz .LBB0_729
	v_max_f32_e32 v0, v0, v0
	v_max_f32_e32 v134, v124, v124
	v_max_f32_e32 v0, v134, v0
	v_cmp_gt_f32_e32 vcc, v0, v124
	s_cbranch_vccz .LBB0_728
	v_sub_f32_e32 v124, v124, v0
	v_exp_f32_e32 v124, v124
	s_nop 0
	v_mul_f32_e32 v117, v117, v124
	v_pk_mul_f32 v[32:33], v[32:33], v[124:125] op_sel_hi:[1,0]
	v_pk_mul_f32 v[30:31], v[30:31], v[124:125] op_sel_hi:[1,0]
	v_pk_mul_f32 v[28:29], v[28:29], v[124:125] op_sel_hi:[1,0]
	v_pk_mul_f32 v[26:27], v[26:27], v[124:125] op_sel_hi:[1,0]
	v_pk_mul_f32 v[24:25], v[24:25], v[124:125] op_sel_hi:[1,0]
	v_pk_mul_f32 v[22:23], v[22:23], v[124:125] op_sel_hi:[1,0]
	v_pk_mul_f32 v[20:21], v[20:21], v[124:125] op_sel_hi:[1,0]
	v_pk_mul_f32 v[18:19], v[18:19], v[124:125] op_sel_hi:[1,0]
	v_pk_mul_f32 v[16:17], v[16:17], v[124:125] op_sel_hi:[1,0]
	v_pk_mul_f32 v[14:15], v[14:15], v[124:125] op_sel_hi:[1,0]
	v_pk_mul_f32 v[12:13], v[12:13], v[124:125] op_sel_hi:[1,0]
	v_pk_mul_f32 v[10:11], v[10:11], v[124:125] op_sel_hi:[1,0]
	v_pk_mul_f32 v[8:9], v[8:9], v[124:125] op_sel_hi:[1,0]
	v_pk_mul_f32 v[6:7], v[6:7], v[124:125] op_sel_hi:[1,0]
	v_pk_mul_f32 v[4:5], v[4:5], v[124:125] op_sel_hi:[1,0]
	v_pk_mul_f32 v[2:3], v[2:3], v[124:125] op_sel_hi:[1,0]
.LBB0_728:
	v_mul_f32_e32 v124, v118, v125
	v_sub_f32_e32 v124, v0, v124
	v_cmp_lt_f32_e32 vcc, s33, v0
	v_sub_f32_e32 v125, v0, v133
	s_nop 0
	v_cndmask_b32_e32 v124, v159, v124, vcc
	v_cndmask_b32_e32 v125, v159, v125, vcc
	v_sub_f32_e32 v134, v80, v124
	v_pk_add_f32 v[68:69], v[68:69], v[124:125] op_sel_hi:[1,0] neg_lo:[0,1] neg_hi:[0,1]
	v_pk_add_f32 v[66:67], v[66:67], v[124:125] op_sel_hi:[1,0] neg_lo:[0,1] neg_hi:[0,1]
	v_sub_f32_e32 v53, v53, v125
	v_sub_f32_e32 v52, v52, v125
	v_sub_f32_e32 v51, v51, v125
	v_sub_f32_e32 v50, v50, v125
	v_exp_f32_e32 v142, v134
	v_add_u32_e32 v134, s9, v130
	v_sub_f32_e32 v141, v65, v125
	v_sub_f32_e32 v143, v64, v125
	v_sub_f32_e32 v147, v63, v125
	v_sub_f32_e32 v139, v62, v125
	v_exp_f32_e32 v62, v66
	v_exp_f32_e32 v64, v50
	v_exp_f32_e32 v63, v67
	v_exp_f32_e32 v65, v51
	v_exp_f32_e32 v66, v68
	v_exp_f32_e32 v68, v52
	v_exp_f32_e32 v67, v69
	v_exp_f32_e32 v69, v53
	ds_read2_b64 v[50:53], v134 offset1:2
	v_sub_f32_e32 v133, v81, v124
	v_sub_f32_e32 v136, v76, v124
	v_sub_f32_e32 v60, v60, v125
	v_sub_f32_e32 v59, v59, v125
	v_sub_f32_e32 v58, v58, v125
	v_exp_f32_e32 v144, v143
	v_exp_f32_e32 v143, v133
	v_add_u32_e32 v133, 0x1000, v134
	v_sub_f32_e32 v137, v79, v124
	v_sub_f32_e32 v138, v78, v124
	v_sub_f32_e32 v146, v77, v124
	v_sub_f32_e32 v79, v75, v124
	v_sub_f32_e32 v78, v74, v124
	v_sub_f32_e32 v75, v73, v124
	v_sub_f32_e32 v74, v72, v124
	v_pk_add_f32 v[70:71], v[70:71], v[124:125] op_sel_hi:[1,0] neg_lo:[0,1] neg_hi:[0,1]
	v_sub_f32_e32 v148, v61, v125
	v_exp_f32_e32 v80, v58
	v_exp_f32_e32 v81, v59
	v_exp_f32_e32 v124, v136
	v_exp_f32_e32 v136, v60
	ds_read2_b64 v[58:61], v133 offset0:32 offset1:34
	v_exp_f32_e32 v70, v70
	v_exp_f32_e32 v71, v71
	v_exp_f32_e32 v74, v74
	v_exp_f32_e32 v75, v75
	v_sub_f32_e32 v57, v57, v125
	v_sub_f32_e32 v56, v56, v125
	v_sub_f32_e32 v55, v55, v125
	v_sub_f32_e32 v54, v54, v125
	v_exp_f32_e32 v72, v54
	v_exp_f32_e32 v73, v55
	v_exp_f32_e32 v76, v56
	v_exp_f32_e32 v77, v57
	v_cvt_pk_bf16_f32 v54, v62, v63
	v_cvt_pk_bf16_f32 v55, v66, v67
	v_cvt_pk_bf16_f32 v56, v70, v71
	v_cvt_pk_bf16_f32 v57, v74, v75
	v_exp_f32_e32 v78, v78
	v_exp_f32_e32 v79, v79
	s_waitcnt lgkmcnt(1)
	v_mfma_f32_32x32x16_bf16 v[2:17], v[50:53], v[54:57], v[2:17]
	ds_read2_b64 v[50:53], v134 offset0:4 offset1:6
	v_exp_f32_e32 v138, v138
	v_exp_f32_e32 v140, v139
	v_exp_f32_e32 v139, v137
	v_exp_f32_e32 v125, v146
	v_pk_add_f32 v[62:63], v[62:63], v[64:65]
	v_pk_add_f32 v[74:75], v[74:75], v[76:77]
	s_waitcnt lgkmcnt(1)
	v_mfma_f32_32x32x16_bf16 v[18:33], v[58:61], v[54:57], v[18:33]
	ds_read2_b64 v[58:61], v133 offset0:36 offset1:38
	v_cvt_pk_bf16_f32 v54, v78, v79
	v_cvt_pk_bf16_f32 v55, v124, v125
	v_cvt_pk_bf16_f32 v56, v138, v139
	v_cvt_pk_bf16_f32 v57, v142, v143
	v_pk_add_f32 v[70:71], v[70:71], v[72:73]
	v_exp_f32_e32 v145, v141
	s_waitcnt lgkmcnt(1)
	v_mfma_f32_32x32x16_bf16 v[2:17], v[50:53], v[54:57], v[2:17]
	v_add_f32_e64 v50, v66, v68
	v_add_f32_e64 v51, v67, v69
	v_exp_f32_e32 v141, v147
	v_pk_mov_b32 v[66:67], v[62:63], v[50:51] op_sel:[1,0]
	v_mov_b32_e32 v63, v51
	ds_read2_b64 v[50:53], v134 offset0:8 offset1:10
	v_exp_f32_e32 v137, v148
	v_pk_add_f32 v[146:147], v[142:143], v[144:145]
	s_waitcnt lgkmcnt(1)
	v_mfma_f32_32x32x16_bf16 v[18:33], v[58:61], v[54:57], v[18:33]
	ds_read2_b64 v[58:61], v133 offset0:40 offset1:42
	v_add_f32_e64 v54, v66, v62
	v_add_f32_e64 v55, v67, v63
	v_cvt_pk_bf16_f32 v56, v72, v73
	v_add_f32_e64 v62, v54, v54
	v_add_f32_e64 v63, v54, v55
	v_cvt_pk_bf16_f32 v54, v64, v65
	v_cvt_pk_bf16_f32 v55, v68, v69
	v_cvt_pk_bf16_f32 v57, v76, v77
	v_pk_add_f32 v[148:149], v[138:139], v[140:141]
	v_pk_add_f32 v[150:151], v[124:125], v[136:137]
	s_waitcnt lgkmcnt(1)
	v_mfma_f32_32x32x16_bf16 v[2:17], v[50:53], v[54:57], v[2:17]
	v_pk_mov_b32 v[50:51], v[70:71], v[74:75] op_sel:[1,0]
	v_mov_b32_e32 v71, v75
	v_pk_add_f32 v[50:51], v[50:51], v[70:71]
	v_pk_add_f32 v[152:153], v[78:79], v[80:81]
	v_pk_add_f32 v[64:65], v[50:51], v[50:51] op_sel_hi:[0,1]
	ds_read2_b64 v[50:53], v134 offset0:12 offset1:14
	v_add_f32_e32 v67, v152, v153
	s_waitcnt lgkmcnt(1)
	v_mfma_f32_32x32x16_bf16 v[18:33], v[58:61], v[54:57], v[18:33]
	ds_read2_b64 v[58:61], v133 offset0:44 offset1:46
	v_cvt_pk_bf16_f32 v54, v80, v81
	v_cvt_pk_bf16_f32 v55, v136, v137
	v_cvt_pk_bf16_f32 v56, v140, v141
	v_cvt_pk_bf16_f32 v57, v144, v145
	v_add_f32_e32 v69, v150, v151
	v_mov_b32_e32 v66, v148
	s_waitcnt lgkmcnt(1)
	v_mfma_f32_32x32x16_bf16 v[2:17], v[50:53], v[54:57], v[2:17]
	v_mov_b32_e32 v68, v149
	v_mov_b32_e32 v62, v146
	v_mov_b32_e32 v64, v147
	v_add_f32_e64 v50, v66, v68
	v_add_f32_e64 v51, v67, v69
	v_pk_add_f32 v[52:53], v[62:63], v[64:65]
	s_nop 0
	v_pk_add_f32 v[50:51], v[50:51], v[52:53]
	s_waitcnt lgkmcnt(0)
	v_mfma_f32_32x32x16_bf16 v[18:33], v[58:61], v[54:57], v[18:33]
	v_add_f32_e32 v50, v50, v51
	v_add_f32_e32 v117, v50, v117
	s_branch .LBB0_730

.LBB0_737:
	s_nop 8
	v_max_f32_e32 v124, v67, v67
	v_max_f32_e32 v133, v66, v66
	v_max_f32_e32 v134, v51, v51
	v_max_f32_e32 v136, v50, v50
	v_max_f32_e32 v124, v133, v124
	v_max_f32_e32 v134, v136, v134
	v_max3_f32 v124, v124, v68, v69
	v_max3_f32 v134, v134, v52, v53
	s_lshl_b32 s0, s11, 6
	v_max3_f32 v124, v124, v70, v71
	v_max3_f32 v134, v134, v54, v55
	v_cvt_f32_u32_e32 v125, s0
	v_max3_f32 v124, v124, v72, v73
	v_max3_f32 v134, v134, v56, v57
	v_max3_f32 v124, v124, v74, v75
	v_max3_f32 v134, v134, v58, v59
	v_max3_f32 v124, v124, v76, v77
	v_max3_f32 v134, v134, v60, v61
	v_max3_f32 v124, v124, v78, v79
	v_max3_f32 v134, v134, v62, v63
	v_fma_f32 v133, v118, v125, v128
	v_max3_f32 v124, v124, v80, v81
	v_max3_f32 v134, v134, v64, v65
	v_fmac_f32_e32 v124, v118, v125
	v_add_f32_e32 v134, v133, v134
	v_max_f32_e32 v124, v124, v134
	v_mov_b32_e32 v134, v124
	s_nop 1
	v_permlane32_swap_b32_e32 v124, v134
	s_waitcnt lgkmcnt(0)
	v_max_f32_e32 v134, v134, v134
	v_max_f32_e32 v124, v124, v134
	v_add_f32_e32 v134, 0xc1c00000, v0
	v_cmp_gt_f32_e32 vcc, v124, v134
	s_cbranch_vccz .LBB0_741
	v_max_f32_e32 v124, v124, v124
	v_max_f32_e32 v134, v0, v0
	v_max_f32_e32 v124, v134, v124
	v_cmp_gt_f32_e32 vcc, v124, v0
	s_cbranch_vccz .LBB0_740
	v_sub_f32_e32 v0, v0, v124
	v_exp_f32_e32 v0, v0
	s_nop 0
	v_mul_f32_e32 v117, v117, v0
	v_pk_mul_f32 v[32:33], v[32:33], v[0:1] op_sel_hi:[1,0]
	v_pk_mul_f32 v[30:31], v[30:31], v[0:1] op_sel_hi:[1,0]
	v_pk_mul_f32 v[28:29], v[28:29], v[0:1] op_sel_hi:[1,0]
	v_pk_mul_f32 v[26:27], v[26:27], v[0:1] op_sel_hi:[1,0]
	v_pk_mul_f32 v[24:25], v[24:25], v[0:1] op_sel_hi:[1,0]
	v_pk_mul_f32 v[22:23], v[22:23], v[0:1] op_sel_hi:[1,0]
	v_pk_mul_f32 v[20:21], v[20:21], v[0:1] op_sel_hi:[1,0]
	v_pk_mul_f32 v[18:19], v[18:19], v[0:1] op_sel_hi:[1,0]
	v_pk_mul_f32 v[16:17], v[16:17], v[0:1] op_sel_hi:[1,0]
	v_pk_mul_f32 v[14:15], v[14:15], v[0:1] op_sel_hi:[1,0]
	v_pk_mul_f32 v[12:13], v[12:13], v[0:1] op_sel_hi:[1,0]
	v_pk_mul_f32 v[10:11], v[10:11], v[0:1] op_sel_hi:[1,0]
	v_pk_mul_f32 v[8:9], v[8:9], v[0:1] op_sel_hi:[1,0]
	v_pk_mul_f32 v[6:7], v[6:7], v[0:1] op_sel_hi:[1,0]
	v_pk_mul_f32 v[4:5], v[4:5], v[0:1] op_sel_hi:[1,0]
	v_pk_mul_f32 v[2:3], v[2:3], v[0:1] op_sel_hi:[1,0]
.LBB0_740:
	v_mul_f32_e32 v0, v118, v125
	v_sub_f32_e32 v0, v124, v0
	v_cmp_lt_f32_e32 vcc, s33, v124
	v_sub_f32_e32 v125, v124, v133
	s_nop 0
	v_cndmask_b32_e32 v0, v159, v0, vcc
	v_cndmask_b32_e32 v125, v159, v125, vcc
	v_sub_f32_e32 v133, v81, v0
	v_sub_f32_e32 v134, v80, v0
	v_sub_f32_e32 v137, v79, v0
	v_sub_f32_e32 v139, v78, v0
	v_sub_f32_e32 v148, v77, v0
	v_sub_f32_e32 v136, v76, v0
	v_sub_f32_e32 v79, v75, v0
	v_sub_f32_e32 v78, v74, v0
	v_sub_f32_e32 v75, v73, v0
	v_sub_f32_e32 v74, v72, v0
	v_pk_add_f32 v[70:71], v[70:71], v[0:1] op_sel_hi:[1,0] neg_lo:[0,1] neg_hi:[0,1]
	v_pk_add_f32 v[68:69], v[68:69], v[0:1] op_sel_hi:[1,0] neg_lo:[0,1] neg_hi:[0,1]
	v_sub_f32_e32 v67, v67, v0
	v_sub_f32_e32 v0, v66, v0
	v_sub_f32_e32 v141, v62, v125
	v_sub_f32_e32 v53, v53, v125
	v_sub_f32_e32 v52, v52, v125
	v_sub_f32_e32 v51, v51, v125
	v_sub_f32_e32 v50, v50, v125
	v_exp_f32_e32 v62, v0
	v_add_u32_e32 v0, s10, v130
	v_sub_f32_e32 v143, v65, v125
	v_sub_f32_e32 v145, v64, v125
	v_sub_f32_e32 v149, v63, v125
	v_exp_f32_e32 v64, v50
	v_exp_f32_e32 v63, v67
	v_exp_f32_e32 v65, v51
	v_exp_f32_e32 v66, v68
	v_exp_f32_e32 v68, v52
	v_exp_f32_e32 v67, v69
	v_exp_f32_e32 v69, v53
	ds_read2_b64 v[50:53], v0 offset1:2
	v_sub_f32_e32 v150, v61, v125
	v_sub_f32_e32 v60, v60, v125
	v_sub_f32_e32 v59, v59, v125
	v_sub_f32_e32 v58, v58, v125
	v_sub_f32_e32 v57, v57, v125
	v_sub_f32_e32 v56, v56, v125
	v_sub_f32_e32 v55, v55, v125
	v_sub_f32_e32 v54, v54, v125
	v_add_u32_e32 v125, 0x1000, v0
	v_exp_f32_e32 v80, v58
	v_exp_f32_e32 v81, v59
	v_exp_f32_e32 v138, v60
	ds_read2_b64 v[58:61], v125 offset0:32 offset1:34
	v_exp_f32_e32 v70, v70
	v_exp_f32_e32 v71, v71
	v_exp_f32_e32 v74, v74
	v_exp_f32_e32 v75, v75
	v_exp_f32_e32 v72, v54
	v_exp_f32_e32 v73, v55
	v_exp_f32_e32 v76, v56
	v_exp_f32_e32 v77, v57
	v_cvt_pk_bf16_f32 v54, v62, v63
	v_cvt_pk_bf16_f32 v55, v66, v67
	v_cvt_pk_bf16_f32 v56, v70, v71
	v_cvt_pk_bf16_f32 v57, v74, v75
	v_exp_f32_e32 v78, v78
	v_exp_f32_e32 v79, v79
	s_waitcnt lgkmcnt(1)
	v_mfma_f32_32x32x16_bf16 v[2:17], v[50:53], v[54:57], v[2:17]
	ds_read2_b64 v[50:53], v0 offset0:4 offset1:6
	v_exp_f32_e32 v136, v136
	v_exp_f32_e32 v140, v139
	v_exp_f32_e32 v142, v141
	v_exp_f32_e32 v141, v137
	v_exp_f32_e32 v144, v134
	v_exp_f32_e32 v146, v145
	s_waitcnt lgkmcnt(1)
	v_mfma_f32_32x32x16_bf16 v[18:33], v[58:61], v[54:57], v[18:33]
	ds_read2_b64 v[58:61], v125 offset0:36 offset1:38
	v_exp_f32_e32 v145, v133
	v_exp_f32_e32 v137, v148
	v_cvt_pk_bf16_f32 v54, v78, v79
	v_cvt_pk_bf16_f32 v56, v140, v141
	v_cvt_pk_bf16_f32 v57, v144, v145
	v_cvt_pk_bf16_f32 v55, v136, v137
	v_pk_add_f32 v[62:63], v[62:63], v[64:65]
	v_pk_add_f32 v[74:75], v[74:75], v[76:77]
	s_waitcnt lgkmcnt(1)
	v_mfma_f32_32x32x16_bf16 v[2:17], v[50:53], v[54:57], v[2:17]
	v_add_f32_e64 v50, v66, v68
	v_add_f32_e64 v51, v67, v69
	v_add_f32_e64 v70, v70, v72
	v_add_f32_e64 v71, v71, v73
	v_pk_mov_b32 v[66:67], v[62:63], v[50:51] op_sel:[1,0]
	v_mov_b32_e32 v63, v51
	ds_read2_b64 v[50:53], v0 offset0:8 offset1:10
	v_exp_f32_e32 v147, v143
	v_exp_f32_e32 v143, v149
	s_waitcnt lgkmcnt(1)
	v_mfma_f32_32x32x16_bf16 v[18:33], v[58:61], v[54:57], v[18:33]
	ds_read2_b64 v[58:61], v125 offset0:40 offset1:42
	v_add_f32_e64 v54, v66, v62
	v_add_f32_e64 v55, v67, v63
	v_cvt_pk_bf16_f32 v56, v72, v73
	v_add_f32_e64 v62, v54, v54
	v_add_f32_e64 v63, v54, v55
	v_cvt_pk_bf16_f32 v54, v64, v65
	v_cvt_pk_bf16_f32 v55, v68, v69
	v_cvt_pk_bf16_f32 v57, v76, v77
	v_exp_f32_e32 v139, v150
	v_pk_add_f32 v[148:149], v[144:145], v[146:147]
	s_waitcnt lgkmcnt(1)
	v_mfma_f32_32x32x16_bf16 v[2:17], v[50:53], v[54:57], v[2:17]
	v_pk_mov_b32 v[50:51], v[70:71], v[74:75] op_sel:[1,0]
	v_mov_b32_e32 v71, v75
	v_pk_add_f32 v[50:51], v[50:51], v[70:71]
	v_pk_add_f32 v[150:151], v[140:141], v[142:143]
	v_pk_add_f32 v[64:65], v[50:51], v[50:51] op_sel_hi:[0,1]
	ds_read2_b64 v[50:53], v0 offset0:12 offset1:14
	v_pk_add_f32 v[152:153], v[136:137], v[138:139]
	s_waitcnt lgkmcnt(1)
	v_mfma_f32_32x32x16_bf16 v[18:33], v[58:61], v[54:57], v[18:33]
	ds_read2_b64 v[58:61], v125 offset0:44 offset1:46
	v_cvt_pk_bf16_f32 v54, v80, v81
	v_cvt_pk_bf16_f32 v55, v138, v139
	v_cvt_pk_bf16_f32 v56, v142, v143
	v_cvt_pk_bf16_f32 v57, v146, v147
	v_pk_add_f32 v[168:169], v[78:79], v[80:81]
	v_add_f32_e32 v69, v152, v153
	s_waitcnt lgkmcnt(1)
	v_mfma_f32_32x32x16_bf16 v[2:17], v[50:53], v[54:57], v[2:17]
	v_add_f32_e32 v67, v168, v169
	v_mov_b32_e32 v66, v150
	v_mov_b32_e32 v68, v151
	v_mov_b32_e32 v62, v148
	v_mov_b32_e32 v64, v149
	v_pk_add_f32 v[50:51], v[66:67], v[68:69]
	v_pk_add_f32 v[52:53], v[62:63], v[64:65]
	s_waitcnt lgkmcnt(0)
	v_mfma_f32_32x32x16_bf16 v[18:33], v[58:61], v[54:57], v[18:33]
	v_add_f32_e64 v50, v50, v52
	v_add_f32_e64 v51, v51, v53
	v_add_f32_e32 v0, v50, v51
	v_add_f32_e32 v117, v0, v117
	s_branch .LBB0_742
